# QKV start de-phased 0/2/4/6 us under the XCD-local GA0->QKV seam
# baseline (speedup 1.0000x reference)
.LBB0_673:
	s_cmp_lt_i32 s56, 11
	s_cselect_b64 s[10:11], -1, 0
	v_lshlrev_b32_e32 v0, 6, v197
	s_and_b64 s[0:1], s[10:11], s[4:5]
	v_and_b32_e32 v168, 0x3c0, v0
	v_lshlrev_b32_e32 v0, 2, v197
	v_lshlrev_b32_e32 v132, 1, v203
	v_and_b32_e32 v169, 32, v0
	s_add_u32 s8, s54, 0x21000000
	s_addc_u32 s9, s55, 0
	s_andn2_b64 vcc, exec, s[0:1]
	v_bitop3_b32 v133, v132, v169, v168 bitop3:0x36
	s_cbranch_vccnz .LBB0_716
	s_bfe_u32 s97, s2, 0x20003
	s_cmp_eq_u32 s97, 0
	s_cbranch_scc1 .Lstag_QKV_done
	s_mul_i32 s97, s97, 1

.Lstag_QKV_done:
	s_add_u32 s12, s54, 0x50000
	s_addc_u32 s13, s55, 0
	s_cmpk_gt_i32 s2, 0x27f
	v_readfirstlane_b32 s5, v197
	v_mbcnt_lo_u32_b32 v0, -1, 0
	v_mbcnt_hi_u32_b32 v0, -1, v0
	s_cbranch_scc1 .LBB0_695
	s_lshr_b32 s18, s5, 6
	s_lshr_b32 s16, s5, 8
	s_lshl_b32 s0, s18, 10
	s_add_u32 s1, s54, 0x1000000
	v_readlane_b32 s6, v248, 5
	s_addc_u32 s40, s55, 0
	v_readlane_b32 s7, v248, 6
	s_movk_i32 s41, 0x51
	s_and_b64 s[6:7], s[6:7], exec
	s_cselect_b32 s4, s41, 0x50
	s_mul_i32 s4, s85, s4
	s_add_i32 s4, s4, s92
	s_mul_hi_i32 s6, s4, 0x66666667
	s_lshr_b32 s7, s6, 31
	s_ashr_i32 s6, s6, 5
	s_add_i32 s6, s6, s7
	s_lshl_b32 s7, s6, 3
	s_mulk_i32 s6, 0x50
	s_sub_i32 s6, s4, s6
	s_bfe_i32 s4, s6, 0x80000
	s_bfe_u32 s4, s4, 0x3000c
	s_add_i32 s14, s6, s4
	s_bfe_i32 s4, s14, 0x80000
	s_and_b32 s14, s14, 0xf8
	s_sub_i32 s6, s6, s14
	s_sext_i32_i16 s4, s4
	s_sext_i32_i8 s6, s6
	s_lshr_b32 s4, s4, 3
	s_add_i32 s6, s7, s6
	s_ashr_i32 s7, s6, 31
	s_bfe_i64 s[20:21], s[4:5], 0x100000
	s_lshl_b64 s[14:15], s[6:7], 20
	s_lshl_b64 s[20:21], s[20:21], 20
	s_add_u32 s50, s1, s20
	s_addc_u32 s51, s40, s21
	s_add_i32 s70, s0, 0
	s_add_i32 m0, s70, 0x10000
	s_waitcnt lgkmcnt(0)
	v_lshl_add_u64 v[0:1], s[50:51], 0, v[154:155]
	global_load_lds_dwordx4 v[0:1], off
	s_add_i32 m0, s70, 0x12000
	s_add_u32 s20, s50, 0x80000
	s_waitcnt vmcnt(0)
	v_lshl_add_u64 v[2:3], s[50:51], 0, v[158:159]
	s_addc_u32 s21, s51, 0
	global_load_lds_dwordx4 v[2:3], off
	s_add_i32 m0, s70, 0x14000
	v_lshl_add_u64 v[4:5], s[20:21], 0, v[154:155]
	global_load_lds_dwordx4 v[4:5], off
	s_add_i32 m0, s70, 0x16000
	s_add_u32 s46, s68, s14
	v_lshl_add_u64 v[4:5], s[20:21], 0, v[158:159]
	s_addc_u32 s47, s69, s15
	s_add_i32 s71, s70, 0x2000
	global_load_lds_dwordx4 v[4:5], off
	v_lshl_add_u64 v[6:7], s[46:47], 0, v[152:153]
	s_mov_b32 m0, s70
	s_add_u32 s14, s46, 0x80000
	global_load_lds_dwordx4 v[6:7], off
	v_lshl_add_u64 v[4:5], s[46:47], 0, v[156:157]
	s_mov_b32 m0, s71
	s_addc_u32 s15, s47, 0
	s_add_i32 s74, s70, 0x4000
	global_load_lds_dwordx4 v[4:5], off
	v_lshl_add_u64 v[8:9], s[14:15], 0, v[152:153]
	s_mov_b32 m0, s74
	s_add_i32 s75, s70, 0x6000
	global_load_lds_dwordx4 v[8:9], off
	v_lshl_add_u64 v[8:9], s[14:15], 0, v[156:157]
	s_mov_b32 m0, s75
	s_cmp_eq_u32 s16, 1
	global_load_lds_dwordx4 v[8:9], off
	s_cselect_b64 s[14:15], -1, 0
	s_cmp_lg_u32 s16, 1
	s_mov_b32 s17, 0
	s_cbranch_scc1 .LBB0_677
	s_barrier
